# layer-0 gate/ffn-gate-up/ffn-down weight conversions deferred into idle WGs of B, G, I last rounds; layer-1 ffn-down into B(1) tail
# speedup vs baseline: 1.0152x; 1.0039x over previous
.LBB0_23:
	s_waitcnt vmcnt(16)
	v_mov_b32_e32 v1, v208
	s_mov_b32 s37, s2
	s_waitcnt lgkmcnt(0)
	s_barrier
.LBB0_28:
	s_add_u32 s33, s22, 0x3378000
	s_mov_b32 s7, 0
	s_addc_u32 s34, s23, 0
	s_movk_i32 s35, 0xffc0
	s_mov_b32 s36, 0x10000
	s_mov_b32 s37, 0x20000
	s_mov_b32 s38, 0x30000
	s_mov_b32 s39, 0x40000
	s_mov_b32 s40, 0x50000
	s_mov_b32 s41, 0x60000
	s_mov_b32 s42, 0x70000
	s_mov_b32 s43, 0x80000
	s_mov_b32 s44, 0x90000
	s_mov_b32 s45, 0xa0000
	s_mov_b32 s46, 0xb0000
	s_mov_b32 s47, 0xc0000
	s_mov_b32 s48, 0xd0000
	s_mov_b32 s49, 0xe0000
	s_mov_b32 s50, 0xf0000
	v_mov_b32_e32 v17, 0
	s_movk_i32 s51, 0x104
	s_mov_b32 s6, s7
	s_barrier
	s_branch .LBB0_30

.LBB0_40:
	s_waitcnt vmcnt(16)
	v_mov_b32_e32 v1, v208
	s_mov_b32 s31, s2
	s_barrier
.LBB0_45:
	s_waitcnt vmcnt(16)
	v_mov_b32_e32 v1, v208
	s_mov_b32 s17, s2
	s_barrier
.LBB0_50:
	s_add_u32 s12, s22, 0x1f8000
	s_mov_b32 s5, 0
	s_addc_u32 s13, s23, 0
	s_movk_i32 s10, 0x2000
	s_movk_i32 s11, 0x4000
	s_movk_i32 s16, 0x6000
	s_mov_b32 s17, 0x8000
	s_mov_b32 s18, 0xa000
	s_mov_b32 s19, 0xc000
	s_mov_b32 s28, 0xe000
	s_mov_b32 s29, 0xf000
	v_mov_b32_e32 v17, 0
	s_movk_i32 s30, 0x104
	s_mov_b32 s4, s5
	s_barrier
	s_branch .LBB0_52

.LBB0_91:
	s_or_b64 exec, exec, s[0:1]
	s_mov_b64 s[0:1], 0

.LBB0_226:
	s_waitcnt vmcnt(0)
	s_barrier
	v_readlane_b32 s86, v255, 41
	s_cmp_lg_u32 s86, 0
	s_cbranch_scc1 .Ldc_g0_skip
	s_movk_i32 s87, 128
	s_cmp_gt_u32 s60, s87
	s_cselect_b32 s87, s87, 0
	s_cmp_lt_u32 s2, s87
	s_cbranch_scc1 .Ldc_g0_skip
	v_writelane_b32 v255, s24, 48
	v_writelane_b32 v255, s28, 49
	v_writelane_b32 v255, s29, 50
	v_writelane_b32 v255, s37, 51
	v_writelane_b32 v255, s40, 52
	v_writelane_b32 v255, s41, 53
	v_writelane_b32 v255, s42, 54
	v_writelane_b32 v255, s43, 55
	v_writelane_b32 v255, s44, 56
	v_writelane_b32 v255, s48, 57
	v_writelane_b32 v255, s49, 58
	v_writelane_b32 v255, s87, 47
	s_sub_u32 s2, s2, s87
	s_sub_u32 s60, s60, s87
	v_readlane_b32 s18, v255, 8
	v_readlane_b32 s19, v255, 9
	s_load_dwordx2 s[42:43], s[18:19], 0xc0
	s_nop 0
	s_load_dwordx2 s[18:19], s[18:19], 0xf0
	s_waitcnt lgkmcnt(0)
.Ldg0_b96:
	s_waitcnt vmcnt(17)
	v_mov_b32_e32 v0, v208
	s_mov_b32 s24, s2
	s_waitcnt lgkmcnt(0)
	s_barrier
	s_cmpk_gt_i32 s24, 0x7ff
	s_cbranch_scc1 .Ldc_g0_done
	s_add_u32 s42, s42, 0
	s_addc_u32 s43, s43, 0
	s_ashr_i32 s26, s24, 31
	s_lshr_b32 s26, s26, 28
	s_add_i32 s26, s24, s26
	s_ashr_i32 s27, s26, 4
	v_and_b32_e32 v20, 63, v0
	s_lshl_b32 s28, s27, 6
	s_waitcnt vmcnt(16)
	v_or_b32_e32 v1, s28, v20
	v_bfe_u32 v23, v0, 4, 1
	v_ashrrev_i32_e32 v26, 6, v0
	v_and_b32_e32 v21, 15, v0
	v_ashrrev_i32_e32 v22, 4, v0
	s_waitcnt vmcnt(15)
	v_and_or_b32 v2, s27, 2, v23
	s_ashr_i32 s27, s28, 2
	v_lshrrev_b32_e32 v0, 1, v1
	s_andn2_b32 s27, s27, 63
	v_and_b32_e32 v0, 48, v0
	s_and_b32 s26, s26, 0x1fffff0
	v_or3_b32 v0, s27, v0, v21
	s_waitcnt vmcnt(3)
	v_lshlrev_b32_e32 v16, 13, v2
	s_sub_i32 s26, s24, s26
	v_lshl_add_u64 v[2:3], s[42:43], 0, v[16:17]
	v_ashrrev_i32_e32 v1, 31, v0
	v_lshl_add_u64 v[0:1], v[0:1], 2, v[2:3]
	v_lshl_add_u32 v2, s26, 7, v26
	v_ashrrev_i32_e32 v3, 31, v2
	v_lshlrev_b64 v[2:3], 15, v[2:3]
	v_lshl_add_u64 v[0:1], v[0:1], 0, v[2:3]
	v_add_co_u32_e32 v2, vcc, s20, v0
	s_mov_b32 s26, 0x100000
	s_nop 0
	v_addc_co_u32_e32 v3, vcc, 0, v1, vcc
	v_add_co_u32_e32 v4, vcc, s64, v0
	v_lshlrev_b32_e32 v16, 4, v21
	s_nop 0
	v_addc_co_u32_e32 v5, vcc, 0, v1, vcc
	v_add_co_u32_e32 v6, vcc, s66, v0
	v_lshl_add_u64 v[18:19], s[18:19], 0, v[16:17]
	s_nop 0
	v_addc_co_u32_e32 v7, vcc, 0, v1, vcc
	v_add_co_u32_e32 v8, vcc, s26, v0
	s_mov_b32 s26, 0x140000
	s_nop 0
	v_addc_co_u32_e32 v9, vcc, 0, v1, vcc
	v_add_co_u32_e32 v10, vcc, s26, v0
	s_mov_b32 s26, 0x180000
	s_nop 0
	v_addc_co_u32_e32 v11, vcc, 0, v1, vcc
	v_add_co_u32_e32 v12, vcc, s26, v0
	s_mov_b32 s26, 0x1c0000
	s_nop 0
	v_addc_co_u32_e32 v13, vcc, 0, v1, vcc
	v_add_co_u32_e32 v14, vcc, s26, v0
	s_mov_b32 s26, 0x200000
	s_waitcnt vmcnt(2)
	v_addc_co_u32_e32 v15, vcc, 0, v1, vcc
	v_add_co_u32_e32 v28, vcc, s26, v0
	s_mov_b32 s26, 0x240000
	s_nop 0
	v_addc_co_u32_e32 v29, vcc, 0, v1, vcc
	v_add_co_u32_e32 v30, vcc, s26, v0
	s_mov_b32 s26, 0x280000
	s_nop 0
	v_addc_co_u32_e32 v31, vcc, 0, v1, vcc
	v_add_co_u32_e32 v32, vcc, s26, v0
	s_mov_b32 s26, 0x2c0000
	s_nop 0
	v_addc_co_u32_e32 v33, vcc, 0, v1, vcc
	v_add_co_u32_e32 v34, vcc, s26, v0
	s_mov_b32 s26, 0x300000
	s_nop 0
	v_addc_co_u32_e32 v35, vcc, 0, v1, vcc
	v_add_co_u32_e32 v36, vcc, s26, v0
	s_mov_b32 s26, 0x340000
	s_nop 0
	v_addc_co_u32_e32 v37, vcc, 0, v1, vcc
	v_add_co_u32_e32 v38, vcc, s26, v0
	s_mov_b32 s26, 0x380000
	s_nop 0
	v_addc_co_u32_e32 v39, vcc, 0, v1, vcc
	v_add_co_u32_e32 v40, vcc, s26, v0
	s_mov_b32 s26, 0x3c0000
	s_nop 0
	v_addc_co_u32_e32 v41, vcc, 0, v1, vcc
	v_add_co_u32_e32 v42, vcc, s26, v0
	s_mov_b64 s[26:27], 0x1378000
	s_nop 0
	v_addc_co_u32_e32 v43, vcc, 0, v1, vcc
	global_load_dword v0, v[0:1], off
	s_nop 0
	global_load_dword v1, v[2:3], off
	s_nop 0
	global_load_dword v2, v[4:5], off
	global_load_dword v3, v[6:7], off
	s_nop 0
	global_load_dword v4, v[8:9], off
	global_load_dword v5, v[10:11], off
	global_load_dword v6, v[12:13], off
	global_load_dword v7, v[14:15], off
	s_nop 0
	global_load_dword v8, v[28:29], off
	global_load_dword v9, v[30:31], off
	global_load_dword v10, v[32:33], off
	global_load_dword v11, v[34:35], off
	global_load_dword v12, v[36:37], off
	global_load_dword v13, v[38:39], off
	global_load_dword v14, v[40:41], off
	global_load_dword v15, v[42:43], off
	v_lshl_add_u64 v[18:19], v[18:19], 0, s[26:27]
	s_movk_i32 s26, 0x104
	s_lshl_b32 s27, s60, 7
	v_mul_lo_u32 v24, v26, s26
	v_mul_u32_u24_e32 v25, 0x820, v21
	s_lshl_b32 s26, s24, 7
	v_add_u32_e32 v26, s27, v26
	s_mov_b64 s[48:49], 0
	s_branch .Ldg0_b99

.Ldc_g0_done:
	s_barrier
	v_readlane_b32 s87, v255, 47
	s_add_u32 s2, s2, s87
	s_add_u32 s60, s60, s87
	v_readlane_b32 s24, v255, 48
	v_readlane_b32 s28, v255, 49
	v_readlane_b32 s29, v255, 50
	v_readlane_b32 s37, v255, 51
	v_readlane_b32 s40, v255, 52
	v_readlane_b32 s41, v255, 53
	v_readlane_b32 s42, v255, 54
	v_readlane_b32 s43, v255, 55
	v_readlane_b32 s44, v255, 56
	v_readlane_b32 s48, v255, 57
	v_readlane_b32 s49, v255, 58
.Ldc_g0_skip:
	v_readlane_b32 s86, v255, 41
	s_cmp_lg_u32 s86, 1
	s_cbranch_scc1 .Ldc_w1_skip
	s_movk_i32 s87, 128
	s_cmp_gt_u32 s60, s87
	s_cselect_b32 s87, s87, 0
	s_cmp_lt_u32 s2, s87
	s_cbranch_scc1 .Ldc_w1_skip
	v_writelane_b32 v255, s24, 48
	v_writelane_b32 v255, s28, 49
	v_writelane_b32 v255, s29, 50
	v_writelane_b32 v255, s37, 51
	v_writelane_b32 v255, s40, 52
	v_writelane_b32 v255, s41, 53
	v_writelane_b32 v255, s42, 54
	v_writelane_b32 v255, s43, 55
	v_writelane_b32 v255, s44, 56
	v_writelane_b32 v255, s87, 47
	s_sub_u32 s2, s2, s87
	s_sub_u32 s60, s60, s87
	v_readlane_b32 s18, v255, 8
	v_readlane_b32 s19, v255, 9
	s_load_dwordx2 s[58:59], s[18:19], 0xe0
	s_nop 0
	s_load_dwordx2 s[18:19], s[18:19], 0xf0
	s_waitcnt lgkmcnt(0)
.Ldw1_b118:
	s_waitcnt vmcnt(17)
	v_mov_b32_e32 v0, v208
	s_mov_b32 s24, s2
	s_barrier
	s_cmpk_gt_i32 s24, 0x57f
	s_cbranch_scc1 .Ldc_w1_done
	s_add_u32 s40, s58, 0x2c00000
	s_mul_hi_i32 s26, s24, 0x2e8ba2e9
	s_addc_u32 s41, s59, 0
	s_lshr_b32 s27, s26, 31
	s_ashr_i32 s26, s26, 3
	s_add_i32 s26, s26, s27
	s_mul_i32 s27, s26, 44
	v_and_b32_e32 v20, 63, v0
	v_ashrrev_i32_e32 v23, 6, v0
	s_sub_i32 s27, s24, s27
	s_waitcnt vmcnt(15)
	v_lshl_or_b32 v2, s26, 6, v20
	s_waitcnt vmcnt(13)
	v_lshl_add_u32 v4, s27, 7, v23
	v_ashrrev_i32_e32 v3, 31, v2
	s_waitcnt vmcnt(12)
	v_ashrrev_i32_e32 v5, 31, v4
	v_lshl_add_u64 v[2:3], v[2:3], 2, s[40:41]
	v_lshlrev_b64 v[4:5], 13, v[4:5]
	v_lshl_add_u64 v[2:3], v[2:3], 0, v[4:5]
	v_add_co_u32_e32 v4, vcc, s67, v2
	s_mov_b32 s26, 0xb0000
	s_nop 0
	v_addc_co_u32_e32 v5, vcc, 0, v3, vcc
	s_waitcnt vmcnt(11)
	v_add_co_u32_e32 v6, vcc, s17, v2
	v_ashrrev_i32_e32 v21, 4, v0
	s_waitcnt vmcnt(10)
	v_addc_co_u32_e32 v7, vcc, 0, v3, vcc
	s_waitcnt vmcnt(9)
	v_add_co_u32_e32 v8, vcc, s74, v2
	s_mov_b32 s27, 0xf0000
	s_waitcnt vmcnt(8)
	v_addc_co_u32_e32 v9, vcc, 0, v3, vcc
	s_waitcnt vmcnt(7)
	v_add_co_u32_e32 v10, vcc, s20, v2
	v_lshlrev_b32_e32 v0, 3, v0
	s_waitcnt vmcnt(6)
	v_addc_co_u32_e32 v11, vcc, 0, v3, vcc
	s_waitcnt vmcnt(5)
	v_add_co_u32_e32 v12, vcc, s75, v2
	v_and_b32_e32 v22, 0x78, v0
	s_waitcnt vmcnt(4)
	v_addc_co_u32_e32 v13, vcc, 0, v3, vcc
	s_waitcnt vmcnt(3)
	v_add_co_u32_e32 v14, vcc, s21, v2
	v_lshlrev_b32_e32 v16, 1, v22
	s_waitcnt vmcnt(2)
	v_addc_co_u32_e32 v15, vcc, 0, v3, vcc
	v_add_co_u32_e32 v24, vcc, s30, v2
	v_lshl_add_u64 v[0:1], s[18:19], 0, v[16:17]
	s_nop 0
	v_addc_co_u32_e32 v25, vcc, 0, v3, vcc
	v_add_co_u32_e32 v26, vcc, s64, v2
	v_mul_u32_u24_e32 v22, 0x104, v22
	s_nop 0
	v_addc_co_u32_e32 v27, vcc, 0, v3, vcc
	v_add_co_u32_e32 v28, vcc, s31, v2
	s_mov_b64 s[42:43], 0
	s_nop 0
	v_addc_co_u32_e32 v29, vcc, 0, v3, vcc
	v_add_co_u32_e32 v30, vcc, s65, v2
	s_nop 1
	v_addc_co_u32_e32 v31, vcc, 0, v3, vcc
	v_add_co_u32_e32 v32, vcc, s26, v2
	s_mov_b32 s26, 0xd0000
	s_nop 0
	v_addc_co_u32_e32 v33, vcc, 0, v3, vcc
	v_add_co_u32_e32 v34, vcc, s66, v2
	s_nop 1
	v_addc_co_u32_e32 v35, vcc, 0, v3, vcc
	v_add_co_u32_e32 v36, vcc, s26, v2
	s_mov_b32 s26, 0xe0000
	s_nop 0
	v_addc_co_u32_e32 v37, vcc, 0, v3, vcc
	v_add_co_u32_e32 v38, vcc, s26, v2
	s_load_dword s28, s[62:63], 0x0
	s_load_dword s26, s[62:63], 0x10
	v_addc_co_u32_e32 v39, vcc, 0, v3, vcc
	v_add_co_u32_e32 v40, vcc, s27, v2
	s_waitcnt lgkmcnt(0)
	s_lshr_b32 s26, s26, 16
	s_cmp_lg_u32 s26, 0
	s_cselect_b64 s[26:27], -1, 0
	s_cmp_lg_u64 s[26:27], 0
	s_addc_u32 s26, s28, 0
	s_mov_b32 s26, s60
	s_mov_b64 s[28:29], 0x6f78000
	v_addc_co_u32_e32 v41, vcc, 0, v3, vcc
	v_lshl_add_u64 v[18:19], v[0:1], 0, s[28:29]
	global_load_dword v0, v[2:3], off
	global_load_dword v1, v[4:5], off
	s_nop 0
	global_load_dword v2, v[6:7], off
	global_load_dword v3, v[8:9], off
	global_load_dword v4, v[10:11], off
	global_load_dword v5, v[12:13], off
	s_nop 0
	global_load_dword v6, v[14:15], off
	global_load_dword v7, v[24:25], off
	global_load_dword v8, v[26:27], off
	global_load_dword v9, v[28:29], off
	global_load_dword v10, v[30:31], off
	global_load_dword v11, v[32:33], off
	global_load_dword v12, v[34:35], off
	global_load_dword v13, v[36:37], off
	global_load_dword v14, v[38:39], off
	global_load_dword v15, v[40:41], off
	s_movk_i32 s27, 0x104
	s_lshl_b32 s36, s26, 7
	v_mul_lo_u32 v16, v23, s27
	s_lshl_b32 s27, s24, 7
	v_add_u32_e32 v23, s36, v23
	s_branch .Ldw1_b121

.Ldc_w1_done:
	s_barrier
	v_readlane_b32 s87, v255, 47
	s_add_u32 s2, s2, s87
	s_add_u32 s60, s60, s87
	v_readlane_b32 s24, v255, 48
	v_readlane_b32 s28, v255, 49
	v_readlane_b32 s29, v255, 50
	v_readlane_b32 s37, v255, 51
	v_readlane_b32 s40, v255, 52
	v_readlane_b32 s41, v255, 53
	v_readlane_b32 s42, v255, 54
	v_readlane_b32 s43, v255, 55
	v_readlane_b32 s44, v255, 56
.Ldc_w1_skip:
.LBB0_227:
	s_waitcnt vmcnt(0)
	s_waitcnt vmcnt(0)
	s_barrier
	s_mov_b64 s[0:1], exec
	v_readlane_b32 s18, v254, 2
	v_readlane_b32 s19, v254, 3
	s_and_b64 s[18:19], s[0:1], s[18:19]
	s_mov_b64 exec, s[18:19]
	s_cbranch_execz .LBB0_279
	v_readlane_b32 s18, v255, 23
	s_waitcnt vmcnt(0) expcnt(0) lgkmcnt(0)
	s_nop 0
	v_mov_b32_e32 v0, s18
	ds_read_b32 v2, v0
	v_readlane_b32 s18, v255, 24
	s_waitcnt lgkmcnt(0)
	v_cmp_ne_u32_e32 vcc, 0, v2
	v_mov_b32_e32 v0, s18
	ds_read_b32 v0, v0
	s_cbranch_vccnz .LBB0_243
	s_mov_b32 s24, 1
	s_branch .LBB0_231

.LBB0_803:
	s_waitcnt vmcnt(0)
	v_readlane_b32 s10, v255, 35
	v_readlane_b32 s11, v255, 36
	s_mov_b64 s[90:91], s[62:63]
	s_barrier
	v_readlane_b32 s86, v255, 41
	s_cmp_lg_u32 s86, 0
	s_cbranch_scc1 .Ldc_u0_skip
	s_movk_i32 s87, 64
	s_cmp_gt_u32 s60, s87
	s_cselect_b32 s87, s87, 0
	s_cmp_lt_u32 s2, s87
	s_cbranch_scc1 .Ldc_u0_skip
	v_writelane_b32 v255, s24, 48
	v_writelane_b32 v255, s26, 49
	v_writelane_b32 v255, s27, 50
	v_writelane_b32 v255, s28, 51
	v_writelane_b32 v255, s29, 52
	v_writelane_b32 v255, s37, 53
	v_writelane_b32 v255, s40, 54
	v_writelane_b32 v255, s41, 55
	v_writelane_b32 v255, s42, 56
	v_writelane_b32 v255, s43, 57
	v_writelane_b32 v255, s48, 58
	v_writelane_b32 v255, s49, 59
	v_writelane_b32 v255, s56, 60
	v_writelane_b32 v255, s57, 61
	v_writelane_b32 v255, s83, 62
	v_writelane_b32 v255, s87, 47
	s_sub_u32 s2, s2, s87
	s_sub_u32 s60, s60, s87
	v_readlane_b32 s18, v255, 8
	v_readlane_b32 s19, v255, 9
	s_load_dwordx2 s[46:47], s[18:19], 0xd0
	s_load_dwordx2 s[56:57], s[18:19], 0xd8
	s_nop 0
	s_load_dwordx2 s[18:19], s[18:19], 0xf0
	s_waitcnt lgkmcnt(0)
.Ldu0_b113:
	s_waitcnt vmcnt(17)
	v_mov_b32_e32 v0, v208
	s_mov_b32 s37, s2
	s_barrier
	s_cmpk_gt_i32 s37, 0xaff
	s_cbranch_scc1 .Ldc_u0_done
	s_add_u32 s24, s46, 0
	s_addc_u32 s26, s47, 0
	s_add_u32 s27, s56, 0
	s_addc_u32 s36, s57, 0
	s_ashr_i32 s28, s37, 31
	s_lshr_b32 s28, s28, 28
	s_add_i32 s28, s37, s28
	s_ashr_i32 s29, s28, 4
	s_and_b32 s28, s28, 0x1fffff0
	s_lshl_b32 s40, s29, 6
	s_sub_i32 s41, s37, s28
	s_bitcmp0_b32 s29, 1
	s_cselect_b32 s42, s26, s36
	s_cselect_b32 s43, s24, s27
	s_ashr_i32 s28, s40, 1
	s_and_b32 s28, s28, 0xffffff80
	s_ashr_i32 s29, s28, 31
	v_and_b32_e32 v20, 63, v0
	s_lshl_b64 s[28:29], s[28:29], 2
	s_add_u32 s28, s43, s28
	s_waitcnt vmcnt(16)
	v_and_or_b32 v1, s40, 64, v20
	v_ashrrev_i32_e32 v24, 6, v0
	s_addc_u32 s29, s42, s29
	s_waitcnt vmcnt(3)
	v_lshlrev_b32_e32 v16, 2, v1
	v_lshl_add_u64 v[2:3], s[28:29], 0, v[16:17]
	v_lshl_add_u32 v1, s41, 7, v24
	s_movk_i32 s28, 0x5800
	v_mad_i64_i32 v[2:3], s[28:29], v1, s28, v[2:3]
	s_mov_b32 s28, 0x2c000
	s_nop 0
	v_add_co_u32_e32 v4, vcc, s28, v2
	s_mov_b32 s28, 0x58000
	s_nop 0
	v_addc_co_u32_e32 v5, vcc, 0, v3, vcc
	v_add_co_u32_e32 v6, vcc, s28, v2
	s_mov_b32 s28, 0x84000
	s_nop 0
	v_addc_co_u32_e32 v7, vcc, 0, v3, vcc
	v_add_co_u32_e32 v8, vcc, s28, v2
	s_mov_b32 s28, 0xb0000
	s_nop 0
	v_addc_co_u32_e32 v9, vcc, 0, v3, vcc
	v_add_co_u32_e32 v10, vcc, s28, v2
	s_mov_b32 s28, 0xdc000
	s_nop 0
	v_addc_co_u32_e32 v11, vcc, 0, v3, vcc
	v_add_co_u32_e32 v12, vcc, s28, v2
	s_mov_b32 s28, 0x108000
	s_nop 0
	v_addc_co_u32_e32 v13, vcc, 0, v3, vcc
	v_add_co_u32_e32 v14, vcc, s28, v2
	s_mov_b32 s28, 0x134000
	s_waitcnt vmcnt(2)
	v_addc_co_u32_e32 v15, vcc, 0, v3, vcc
	v_add_co_u32_e32 v26, vcc, s28, v2
	s_mov_b32 s28, 0x160000
	s_nop 0
	v_addc_co_u32_e32 v27, vcc, 0, v3, vcc
	v_add_co_u32_e32 v28, vcc, s28, v2
	s_mov_b32 s28, 0x18c000
	s_nop 0
	v_addc_co_u32_e32 v29, vcc, 0, v3, vcc
	v_add_co_u32_e32 v30, vcc, s28, v2
	s_mov_b32 s28, 0x1b8000
	s_nop 0
	v_addc_co_u32_e32 v31, vcc, 0, v3, vcc
	v_add_co_u32_e32 v32, vcc, s28, v2
	s_mov_b32 s28, 0x1e4000
	s_nop 0
	v_addc_co_u32_e32 v33, vcc, 0, v3, vcc
	v_add_co_u32_e32 v34, vcc, s28, v2
	s_mov_b32 s28, 0x210000
	s_nop 0
	v_addc_co_u32_e32 v35, vcc, 0, v3, vcc
	v_add_co_u32_e32 v36, vcc, s28, v2
	s_mov_b32 s28, 0x23c000
	s_nop 0
	v_addc_co_u32_e32 v37, vcc, 0, v3, vcc
	v_add_co_u32_e32 v38, vcc, s28, v2
	s_mov_b32 s28, 0x268000
	s_nop 0
	v_addc_co_u32_e32 v39, vcc, 0, v3, vcc
	v_add_co_u32_e32 v40, vcc, s28, v2
	s_load_dword s40, s[62:63], 0x0
	s_load_dword s28, s[62:63], 0x10
	v_ashrrev_i32_e32 v21, 4, v0
	v_lshlrev_b32_e32 v0, 3, v0
	v_addc_co_u32_e32 v41, vcc, 0, v3, vcc
	s_waitcnt lgkmcnt(0)
	s_lshr_b32 s28, s28, 16
	s_mov_b32 s29, 0x294000
	s_cmp_lg_u32 s28, 0
	v_and_b32_e32 v23, 0x78, v0
	v_add_co_u32_e32 v42, vcc, s29, v2
	s_cselect_b64 s[28:29], -1, 0
	v_lshlrev_b32_e32 v16, 1, v23
	s_cmp_lg_u64 s[28:29], 0
	v_lshl_add_u64 v[0:1], s[18:19], 0, v[16:17]
	s_mov_b64 s[28:29], 0x4378000
	v_addc_co_u32_e32 v43, vcc, 0, v3, vcc
	v_lshl_add_u64 v[18:19], v[0:1], 0, s[28:29]
	global_load_dword v0, v[2:3], off
	global_load_dword v1, v[4:5], off
	s_nop 0
	global_load_dword v2, v[6:7], off
	global_load_dword v3, v[8:9], off
	global_load_dword v4, v[10:11], off
	global_load_dword v5, v[12:13], off
	s_nop 0
	global_load_dword v6, v[14:15], off
	global_load_dword v7, v[26:27], off
	global_load_dword v8, v[28:29], off
	global_load_dword v9, v[30:31], off
	global_load_dword v10, v[32:33], off
	global_load_dword v11, v[34:35], off
	global_load_dword v12, v[36:37], off
	global_load_dword v13, v[38:39], off
	global_load_dword v14, v[40:41], off
	global_load_dword v15, v[42:43], off
	s_addc_u32 s42, s40, 0
	s_mov_b32 s42, s60
	s_movk_i32 s28, 0x104
	s_lshl_b32 s44, s42, 7
	v_mul_lo_u32 v22, v24, s28
	v_mul_u32_u24_e32 v23, 0x104, v23
	s_lshl_b32 s43, s37, 7
	v_add_u32_e32 v24, s44, v24
	s_mov_b64 s[40:41], 0
	s_branch .Ldu0_b116

.Ldc_u0_done:
	s_barrier
	v_readlane_b32 s87, v255, 47
	s_add_u32 s2, s2, s87
	s_add_u32 s60, s60, s87
	v_readlane_b32 s24, v255, 48
	v_readlane_b32 s26, v255, 49
	v_readlane_b32 s27, v255, 50
	v_readlane_b32 s28, v255, 51
	v_readlane_b32 s29, v255, 52
	v_readlane_b32 s37, v255, 53
	v_readlane_b32 s40, v255, 54
	v_readlane_b32 s41, v255, 55
	v_readlane_b32 s42, v255, 56
	v_readlane_b32 s43, v255, 57
	v_readlane_b32 s48, v255, 58
	v_readlane_b32 s49, v255, 59
	v_readlane_b32 s56, v255, 60
	v_readlane_b32 s57, v255, 61
	v_readlane_b32 s83, v255, 62
.Ldc_u0_skip:
.LBB0_804:
	s_waitcnt vmcnt(0)
	s_waitcnt vmcnt(0) lgkmcnt(0)
	s_barrier
	s_mov_b64 s[0:1], exec
	v_readlane_b32 s14, v254, 2
	v_readlane_b32 s15, v254, 3
	s_and_b64 s[14:15], s[0:1], s[14:15]
	s_mov_b64 exec, s[14:15]
	s_cbranch_execz .LBB0_856
	v_readlane_b32 s14, v255, 23
	s_waitcnt vmcnt(0) expcnt(0) lgkmcnt(0)
	s_nop 0
	v_mov_b32_e32 v0, s14
	ds_read_b32 v2, v0
	v_readlane_b32 s14, v255, 24
	s_waitcnt lgkmcnt(0)
	v_cmp_ne_u32_e32 vcc, 0, v2
	v_mov_b32_e32 v0, s14
	ds_read_b32 v0, v0
	s_cbranch_vccnz .LBB0_820
	s_mov_b32 s26, 1
	s_branch .LBB0_808

.LBB0_926:
	s_waitcnt vmcnt(0)
	s_barrier
	v_readlane_b32 s86, v255, 41
	s_cmp_lg_u32 s86, 0
	s_cbranch_scc1 .Ldc_w0_skip
	s_movk_i32 s87, 96
	s_cmp_gt_u32 s60, s87
	s_cselect_b32 s87, s87, 0
	s_cmp_lt_u32 s2, s87
	s_cbranch_scc1 .Ldc_w0_skip
	v_writelane_b32 v255, s24, 48
	v_writelane_b32 v255, s26, 49
	v_writelane_b32 v255, s27, 50
	v_writelane_b32 v255, s28, 51
	v_writelane_b32 v255, s29, 52
	v_writelane_b32 v255, s37, 53
	v_writelane_b32 v255, s40, 54
	v_writelane_b32 v255, s41, 55
	v_writelane_b32 v255, s42, 56
	v_writelane_b32 v255, s43, 57
	v_writelane_b32 v255, s56, 58
	v_writelane_b32 v255, s83, 59
	v_writelane_b32 v255, s87, 47
	s_sub_u32 s2, s2, s87
	s_sub_u32 s60, s60, s87
	v_readlane_b32 s18, v255, 8
	v_readlane_b32 s19, v255, 9
	s_load_dwordx2 s[58:59], s[18:19], 0xe0
	s_nop 0
	s_load_dwordx2 s[18:19], s[18:19], 0xf0
	s_waitcnt lgkmcnt(0)
.Ldw0_b118:
	s_waitcnt vmcnt(17)
	v_mov_b32_e32 v0, v208
	s_mov_b32 s24, s2
	s_barrier
	s_cmpk_gt_i32 s24, 0x57f
	s_cbranch_scc1 .Ldc_w0_done
	s_add_u32 s40, s58, 0
	s_mul_hi_i32 s26, s24, 0x2e8ba2e9
	s_addc_u32 s41, s59, 0
	s_lshr_b32 s27, s26, 31
	s_ashr_i32 s26, s26, 3
	s_add_i32 s26, s26, s27
	s_mul_i32 s27, s26, 44
	v_and_b32_e32 v20, 63, v0
	v_ashrrev_i32_e32 v23, 6, v0
	s_sub_i32 s27, s24, s27
	s_waitcnt vmcnt(15)
	v_lshl_or_b32 v2, s26, 6, v20
	s_waitcnt vmcnt(13)
	v_lshl_add_u32 v4, s27, 7, v23
	v_ashrrev_i32_e32 v3, 31, v2
	s_waitcnt vmcnt(12)
	v_ashrrev_i32_e32 v5, 31, v4
	v_lshl_add_u64 v[2:3], v[2:3], 2, s[40:41]
	v_lshlrev_b64 v[4:5], 13, v[4:5]
	v_lshl_add_u64 v[2:3], v[2:3], 0, v[4:5]
	v_add_co_u32_e32 v4, vcc, s67, v2
	s_mov_b32 s26, 0xb0000
	s_nop 0
	v_addc_co_u32_e32 v5, vcc, 0, v3, vcc
	s_waitcnt vmcnt(11)
	v_add_co_u32_e32 v6, vcc, s17, v2
	v_ashrrev_i32_e32 v21, 4, v0
	s_waitcnt vmcnt(10)
	v_addc_co_u32_e32 v7, vcc, 0, v3, vcc
	s_waitcnt vmcnt(9)
	v_add_co_u32_e32 v8, vcc, s74, v2
	s_mov_b32 s27, 0xf0000
	s_waitcnt vmcnt(8)
	v_addc_co_u32_e32 v9, vcc, 0, v3, vcc
	s_waitcnt vmcnt(7)
	v_add_co_u32_e32 v10, vcc, s20, v2
	v_lshlrev_b32_e32 v0, 3, v0
	s_waitcnt vmcnt(6)
	v_addc_co_u32_e32 v11, vcc, 0, v3, vcc
	s_waitcnt vmcnt(5)
	v_add_co_u32_e32 v12, vcc, s75, v2
	v_and_b32_e32 v22, 0x78, v0
	s_waitcnt vmcnt(4)
	v_addc_co_u32_e32 v13, vcc, 0, v3, vcc
	s_waitcnt vmcnt(3)
	v_add_co_u32_e32 v14, vcc, s21, v2
	v_lshlrev_b32_e32 v16, 1, v22
	s_waitcnt vmcnt(2)
	v_addc_co_u32_e32 v15, vcc, 0, v3, vcc
	v_add_co_u32_e32 v24, vcc, s30, v2
	v_lshl_add_u64 v[0:1], s[18:19], 0, v[16:17]
	s_nop 0
	v_addc_co_u32_e32 v25, vcc, 0, v3, vcc
	v_add_co_u32_e32 v26, vcc, s64, v2
	v_mul_u32_u24_e32 v22, 0x104, v22
	s_nop 0
	v_addc_co_u32_e32 v27, vcc, 0, v3, vcc
	v_add_co_u32_e32 v28, vcc, s31, v2
	s_mov_b64 s[42:43], 0
	s_nop 0
	v_addc_co_u32_e32 v29, vcc, 0, v3, vcc
	v_add_co_u32_e32 v30, vcc, s65, v2
	s_nop 1
	v_addc_co_u32_e32 v31, vcc, 0, v3, vcc
	v_add_co_u32_e32 v32, vcc, s26, v2
	s_mov_b32 s26, 0xd0000
	s_nop 0
	v_addc_co_u32_e32 v33, vcc, 0, v3, vcc
	v_add_co_u32_e32 v34, vcc, s66, v2
	s_nop 1
	v_addc_co_u32_e32 v35, vcc, 0, v3, vcc
	v_add_co_u32_e32 v36, vcc, s26, v2
	s_mov_b32 s26, 0xe0000
	s_nop 0
	v_addc_co_u32_e32 v37, vcc, 0, v3, vcc
	v_add_co_u32_e32 v38, vcc, s26, v2
	s_load_dword s28, s[62:63], 0x0
	s_load_dword s26, s[62:63], 0x10
	v_addc_co_u32_e32 v39, vcc, 0, v3, vcc
	v_add_co_u32_e32 v40, vcc, s27, v2
	s_waitcnt lgkmcnt(0)
	s_lshr_b32 s26, s26, 16
	s_cmp_lg_u32 s26, 0
	s_cselect_b64 s[26:27], -1, 0
	s_cmp_lg_u64 s[26:27], 0
	s_addc_u32 s26, s28, 0
	s_mov_b32 s26, s60
	s_mov_b64 s[28:29], 0x6f78000
	v_addc_co_u32_e32 v41, vcc, 0, v3, vcc
	v_lshl_add_u64 v[18:19], v[0:1], 0, s[28:29]
	global_load_dword v0, v[2:3], off
	global_load_dword v1, v[4:5], off
	s_nop 0
	global_load_dword v2, v[6:7], off
	global_load_dword v3, v[8:9], off
	global_load_dword v4, v[10:11], off
	global_load_dword v5, v[12:13], off
	s_nop 0
	global_load_dword v6, v[14:15], off
	global_load_dword v7, v[24:25], off
	global_load_dword v8, v[26:27], off
	global_load_dword v9, v[28:29], off
	global_load_dword v10, v[30:31], off
	global_load_dword v11, v[32:33], off
	global_load_dword v12, v[34:35], off
	global_load_dword v13, v[36:37], off
	global_load_dword v14, v[38:39], off
	global_load_dword v15, v[40:41], off
	s_movk_i32 s27, 0x104
	s_lshl_b32 s36, s26, 7
	v_mul_lo_u32 v16, v23, s27
	s_lshl_b32 s27, s24, 7
	v_add_u32_e32 v23, s36, v23
	s_branch .Ldw0_b121

.Ldc_w0_done:
	s_barrier
	v_readlane_b32 s87, v255, 47
	s_add_u32 s2, s2, s87
	s_add_u32 s60, s60, s87
	v_readlane_b32 s24, v255, 48
	v_readlane_b32 s26, v255, 49
	v_readlane_b32 s27, v255, 50
	v_readlane_b32 s28, v255, 51
	v_readlane_b32 s29, v255, 52
	v_readlane_b32 s37, v255, 53
	v_readlane_b32 s40, v255, 54
	v_readlane_b32 s41, v255, 55
	v_readlane_b32 s42, v255, 56
	v_readlane_b32 s43, v255, 57
	v_readlane_b32 s56, v255, 58
	v_readlane_b32 s83, v255, 59
.Ldc_w0_skip:
.LBB0_927:
	s_waitcnt vmcnt(0)
	s_waitcnt vmcnt(0)
	s_barrier
	s_mov_b64 s[0:1], exec
	v_readlane_b32 s14, v254, 2
	v_readlane_b32 s15, v254, 3
	v_readlane_b32 s62, v255, 37
	s_and_b64 s[14:15], s[0:1], s[14:15]
	v_readlane_b32 s63, v255, 38
	s_mov_b64 exec, s[14:15]
	s_cbranch_execz .LBB0_979
	v_readlane_b32 s14, v255, 23
	s_waitcnt vmcnt(0) expcnt(0) lgkmcnt(0)
	s_nop 0
	v_mov_b32_e32 v0, s14
	ds_read_b32 v2, v0
	v_readlane_b32 s14, v255, 24
	s_waitcnt lgkmcnt(0)
	v_cmp_ne_u32_e32 vcc, 0, v2
	v_mov_b32_e32 v0, s14
	ds_read_b32 v0, v0
	s_cbranch_vccnz .LBB0_943
	s_mov_b32 s26, 1
	s_branch .LBB0_931
